# e51 + the three in_w transpose items of each P0 transpose workgroup moved to the 96 S5-table workgroups (two items each at the end of their P1)
# speedup vs baseline: 1.0005x; 1.0005x over previous
; #define LAS __attribute__((address_space(3)))
; #define SUB(i, ...) do { if (PROBE_PH == phk && PROBE_SUB == (i)) { __syncthreads(); tp0 = __builtin_amdgcn_s_memrealtime(); } __VA_ARGS__ if (PROBE_PH == phk && PROBE_SUB == (i)) { asm volatile("s_waitcnt vmcnt(0)" ::: "memory"); __syncthreads(); tp1 = __builtin_amdgcn_s_memrealtime(); } } while (0)
; __device__ __forceinline__ void transpose_dispatch(int it, const float* in_w, const float* out_w, const float* glu_w, const float* pool_w, unsigned char* ws, LAS float* scr, int lane) {
;     if (it < 4 * TI_POOL1) { const int pg = it / TI_POOL1; transpose_item(pool_w + pg * 65536, 256, 256, 256, (f16*)(ws + WS_WPOOL) + pg * 65536, scr, it % TI_POOL1, lane); return; } it -= 4 * TI_POOL1;
;     if (it < TI_RAW) { convert_item(in_w, (f16*)(ws + WS_WRAW), it, lane); return; } it -= TI_RAW;
;     if (it < TI_IN) { transpose_item(in_w + 1024, D, 4096, 3072, (f16*)(ws + WS_WIN) + (size_t)1024 * D, scr, it, lane); return; } it -= TI_IN;
;     if (it < TI_OUT) { transpose_item(out_w, D, D, D, (f16*)(ws + WS_WOUT), scr, it, lane); return; } it -= TI_OUT;
;     transpose_item(glu_w, SW, 2 * SW, 2 * SW, (f16*)(ws + WS_WGLU), scr, it, lane);
; __global__ void __launch_bounds__(NTHREADS, 2) mk_fwd(Args a) {
;     ...
;         SUB(2, if (vcu < 128) transpose_dispatch((320 + vcu) * 8 + wave, a.in[7], a.in[20], a.in[18], a.in[8], a.ws, scr, lane);
.LBB0_230:
	s_cmp_gt_u32 s100, 3
	s_cbranch_scc1 .Lp1_a_next
	s_cmp_lg_u32 s100, 0
	s_cbranch_scc1 .Lp1_stub_old
	s_cmpk_gt_i32 s16, 0xbf
	s_cbranch_scc1 .Lp1_stub_old
	s_cmpk_gt_i32 s81, 0x7f
	s_cbranch_scc1 .Lp1_stub_old
	s_mov_b32 s100, 4
	s_branch .Lp1_a_item
.Lp1_a_next:
	s_add_i32 s100, s100, 1
	s_cmp_gt_u32 s100, 5
	s_cbranch_scc1 .Lp1_stub_old
.Lp1_a_item:
	s_lshr_b32 s6, s81, 5
	s_mul_i32 s6, s6, 24
	s_and_b32 s7, s81, 31
	s_add_i32 s6, s6, s7
	s_lshl_b32 s6, s6, 1
	s_add_i32 s6, s6, s100
	s_add_i32 s6, s6, 0xffffff0c
	s_lshl_b32 s6, s6, 3
	s_add_i32 s6, s6, s53
	s_add_u32 s0, s50, 0x2000000
	s_addc_u32 s1, s51, 0
	s_add_u32 s4, s50, 0x13600000
	s_addc_u32 s5, s51, 0
	s_mul_i32 s28, s53, 0x2100
	s_mov_b32 s13, 0
	s_mov_b64 s[2:3], -1
	s_branch .LBB0_213
